# gz_phase: 24 fragment loads per k-group issued together (4 round trips instead of ~24)
# baseline (speedup 1.0000x reference)
; __device__ __forceinline__ f32x4 mfma16(bf16x8 a, bf16x8 b, f32x4 c) { return __builtin_amdgcn_mfma_f32_16x16x32_bf16(a, b, c, 0, 0, 0); }
; __device__ __forceinline__ void gz_phase(CArgs& a, int l, int panel) {
;     int tid_ = threadIdx.x; asm volatile("" : "+v"(tid_));
;     const int lane = tid_ & 63, wave = __builtin_amdgcn_readfirstlane(tid_ >> 6), fr = lane & 15, fq = lane >> 4;
;     unsigned char* ws = a.ws;
;     const bf16_t* Hb = (const bf16_t*)(ws + WS_HB) + (size_t)panel * 256 * DM + (size_t)(wave * 32 + fr) * DM + 8 * fq;
;     const bf16_t* Wt = (const bf16_t*)(ws + WS_WIN) + (size_t)l * DINP * DM + (size_t)(C_GZ + fr) * DM + 8 * fq;
;     f32x4 acc0 = (f32x4){0.f, 0.f, 0.f, 0.f}, acc1 = acc0;
; #pragma unroll 8
;     for (int ks = 0; ks < 32; ++ks) {
;         const bf16x8 wf = *(const bf16x8*)(Wt + 32 * ks);
;         acc0 = mfma16(wf, *(const bf16x8*)(Hb + 32 * ks), acc0);
;         acc1 = mfma16(wf, *(const bf16x8*)(Hb + 16 * DM + 32 * ks), acc1);
;     }
.LBB0_121:
	v_lshl_add_u64 v[112:113], v[12:13], 0, s[20:21]
	v_add_co_u32_e32 v114, vcc, 0x6000000, v112
	s_nop 1
	v_addc_co_u32_e32 v115, vcc, 0, v113, vcc
	v_add_co_u32_e32 v116, vcc, 0x6008000, v112
	s_nop 1
	v_addc_co_u32_e32 v117, vcc, 0, v113, vcc
	v_lshl_add_u64 v[112:113], v[14:15], 0, s[20:21]
	global_load_dwordx4 v[16:19], v[112:113], off offset:-256
	global_load_dwordx4 v[20:23], v[112:113], off offset:-192
	global_load_dwordx4 v[24:27], v[112:113], off offset:-128
	global_load_dwordx4 v[28:31], v[112:113], off offset:-64
	global_load_dwordx4 v[32:35], v[112:113], off
	global_load_dwordx4 v[36:39], v[112:113], off offset:64
	global_load_dwordx4 v[40:43], v[112:113], off offset:128
	global_load_dwordx4 v[44:47], v[112:113], off offset:192
	global_load_dwordx4 v[48:51], v[114:115], off
	global_load_dwordx4 v[52:55], v[114:115], off offset:64
	global_load_dwordx4 v[56:59], v[114:115], off offset:128
	global_load_dwordx4 v[60:63], v[114:115], off offset:192
	global_load_dwordx4 v[64:67], v[114:115], off offset:256
	global_load_dwordx4 v[68:71], v[114:115], off offset:320
	global_load_dwordx4 v[72:75], v[114:115], off offset:384
	global_load_dwordx4 v[76:79], v[114:115], off offset:448
	global_load_dwordx4 v[80:83], v[116:117], off
	global_load_dwordx4 v[84:87], v[116:117], off offset:64
	global_load_dwordx4 v[88:91], v[116:117], off offset:128
	global_load_dwordx4 v[92:95], v[116:117], off offset:192
	global_load_dwordx4 v[96:99], v[116:117], off offset:256
	global_load_dwordx4 v[100:103], v[116:117], off offset:320
	global_load_dwordx4 v[104:107], v[116:117], off offset:384
	global_load_dwordx4 v[108:111], v[116:117], off offset:448
	s_add_u32 s20, s20, 0x200
	s_addc_u32 s21, s21, 0
	s_cmpk_lg_i32 s20, 0x800
	s_waitcnt vmcnt(0)
	v_mfma_f32_16x16x32_bf16 v[2:5], v[16:19], v[48:51], v[2:5]
	v_mfma_f32_16x16x32_bf16 v[6:9], v[16:19], v[80:83], v[6:9]
	v_mfma_f32_16x16x32_bf16 v[2:5], v[20:23], v[52:55], v[2:5]
	v_mfma_f32_16x16x32_bf16 v[6:9], v[20:23], v[84:87], v[6:9]
	v_mfma_f32_16x16x32_bf16 v[2:5], v[24:27], v[56:59], v[2:5]
	v_mfma_f32_16x16x32_bf16 v[6:9], v[24:27], v[88:91], v[6:9]
	v_mfma_f32_16x16x32_bf16 v[2:5], v[28:31], v[60:63], v[2:5]
	v_mfma_f32_16x16x32_bf16 v[6:9], v[28:31], v[92:95], v[6:9]
	v_mfma_f32_16x16x32_bf16 v[2:5], v[32:35], v[64:67], v[2:5]
	v_mfma_f32_16x16x32_bf16 v[6:9], v[32:35], v[96:99], v[6:9]
	v_mfma_f32_16x16x32_bf16 v[2:5], v[36:39], v[68:71], v[2:5]
	v_mfma_f32_16x16x32_bf16 v[6:9], v[36:39], v[100:103], v[6:9]
	v_mfma_f32_16x16x32_bf16 v[2:5], v[40:43], v[72:75], v[2:5]
	v_mfma_f32_16x16x32_bf16 v[6:9], v[40:43], v[104:107], v[6:9]
	v_mfma_f32_16x16x32_bf16 v[2:5], v[44:47], v[76:79], v[2:5]
	v_mfma_f32_16x16x32_bf16 v[6:9], v[44:47], v[108:111], v[6:9]
	s_cbranch_scc1 .LBB0_121
; #define PG8_STAGE(bufoff, gbase, voff) do { _Pragma("unroll") for (int _i = 0; _i < 2; ++_i) \
;         __builtin_amdgcn_global_load_lds((const unsigned*)((const char*)(gbase) + (voff)[_i]), (LAS unsigned*)(lds + (bufoff) + ldsw + _i * 8192), 16, 0, 0); } while (0)
; #define PG8_BAR __builtin_amdgcn_s_barrier()
; template <class Epi, class Sched>
; __device__ __forceinline__ void gemm_phase(LAS unsigned char* lds, const Gemm g, const Sched& S, const Epi& E) {
;     ...
;     int K = g.K; asm volatile("" : "+s"(K));
;     const int nt = K / BK;
;     unsigned voffA[2], voffB[2];
; #pragma unroll
;     for (int i = 0; i < 2; ++i) { int R, C; stage_rc(tid * 16 + i * 8192, R, C); const int Rb = Epi::PERM ? ((R & ~31) + perm32(R & 31)) : R;
;         voffA[i] = (unsigned)(R * K + C) * 2u; voffB[i] = (unsigned)(Rb * K + C) * 2u; }
;     const size_t kstep = (size_t)(BK * 2);
;     const size_t hstep = (size_t)HALF * K * 2;
;     const size_t tstep = 2 * hstep;
;     const unsigned ldsw = (unsigned)wid * 1024u;
;     const int aoff = lds_byte(wr * 64 + fr, fq * 8), boff = lds_byte(wc * 32 + fr, fq * 8);
;     ...
;     Unit cur, nxt; int ui = 0;
;     if (!S.next(0, cur)) return;
;     f32x4 acc[2][2][4][2];
; #pragma unroll
;     for (int a = 0; a < 2; ++a)
; #pragma unroll
;         for (int b = 0; b < 2; ++b)
; #pragma unroll
;             for (int m = 0; m < 4; ++m)
; #pragma unroll
;                 for (int n = 0; n < 2; ++n) acc[a][b][m][n] = (f32x4){0.f, 0.f, 0.f, 0.f};
;     bf16x8 At[4][2], B0[2][2], B1[2][2];
;     const char* cA = (const char*)g.A + (size_t)cur.pm * tstep; const char* cB = (const char*)g.Bt + (size_t)cur.pn * tstep;
;     S.a_ready(cur);
;     PG8_STAGE(PG8_SB(0, 0), cB, voffB); PG8_STAGE(PG8_SB(0, 1), cB + hstep, voffB); PG8_STAGE(PG8_SA(0, 0), cA, voffA); PG8_STAGE(PG8_SA(0, 1), cA + hstep, voffA);
;     if (wr == 1) PG8_BAR;
; __device__ __forceinline__ void gz_phase(CArgs& a, int l, int panel) {
;     ...
;     unsigned char* Zp = ws + WS_PANEL + (size_t)panel * PANEL_BYTES + P_Z;
;     u32x2 w0, w1; w0.x = pk2(acc0[0], acc0[1]); w0.y = pk2(acc0[2], acc0[3]); w1.x = pk2(acc1[0], acc1[1]); w1.y = pk2(acc1[2], acc1[3]);
;     *(u32x2*)(Zp + (size_t)(wave * 32 + fr) * ZROWB + (C_GZ + 4 * fq) * 2) = w0;
;     *(u32x2*)(Zp + (size_t)(wave * 32 + 16 + fr) * ZROWB + (C_GZ + 4 * fq) * 2) = w1;
	s_add_u32 s1, s10, s88
	s_addc_u32 s3, s11, s89
	s_add_u32 s2, s1, 0xe000000
	s_addc_u32 s3, s3, 0
	v_lshrrev_b32_e32 v0, 1, v0
	v_cvt_pk_bf16_f32 v2, v2, v3
	v_cvt_pk_bf16_f32 v3, v4, v5
	v_cvt_pk_bf16_f32 v4, v6, v7
	s_nop 1
	v_mov_b64_e32 v[6:7], s[2:3]
	v_cvt_pk_bf16_f32 v5, v8, v9
	v_mad_i64_i32 v[8:9], s[2:3], v10, s90, v[6:7]
	v_and_or_b32 v0, v0, 24, v233
	v_lshl_add_u64 v[8:9], v[8:9], 0, v[0:1]
	global_store_dwordx2 v[8:9], v[2:3], off
	v_or_b32_e32 v2, 16, v10
	v_mad_i64_i32 v[2:3], s[2:3], v2, s90, v[6:7]
	v_readlane_b32 s2, v249, 0
	v_lshl_add_u64 v[2:3], v[2:3], 0, v[0:1]
	v_readlane_b32 s3, v249, 1
	v_mov_b32_e32 v14, v189
	global_store_dwordx2 v[2:3], v[4:5], off
	s_load_dwordx2 s[44:45], s[2:3], 0xf8
	s_mov_b32 s5, 0x7fffffe0
	v_lshlrev_b32_e32 v0, 4, v14
	v_add_u32_e32 v2, 0x2000, v0
	v_ashrrev_i32_e32 v3, 31, v2
	v_lshrrev_b32_e32 v3, 22, v3
	v_add_u32_e32 v3, v2, v3
	v_ashrrev_i32_e32 v3, 10, v3
	v_mul_i32_i24_e32 v4, 0x400, v3
	v_sub_u32_e32 v2, v2, v4
	v_lshrrev_b32_e32 v4, 4, v2
	v_bitop3_b32 v2, v4, v2, 32 bitop3:0x6c
	v_ashrrev_i32_e32 v4, 31, v2
	v_lshrrev_b32_e32 v4, 26, v4
	v_add_u32_e32 v4, v2, v4
	v_lshlrev_b32_e32 v6, 3, v3
	v_ashrrev_i32_e32 v5, 6, v4
	v_and_b32_e32 v6, -16, v6
	v_lshlrev_b32_e32 v3, 5, v3
	v_add_u32_e32 v6, v5, v6
	v_and_b32_e32 v15, 32, v3
	v_and_b32_e32 v3, 0xc0, v4
	v_and_b32_e32 v5, 3, v5
	v_lshrrev_b32_e32 v7, 2, v6
	v_lshlrev_b32_e32 v8, 1, v6
	v_sub_u32_e32 v2, v2, v3
	v_and_or_b32 v5, v6, s5, v5
	v_and_b32_e32 v7, 4, v7
	v_and_b32_e32 v8, 24, v8
	v_ashrrev_i16_sdwa v2, v227, sext(v2) dst_sel:DWORD dst_unused:UNUSED_PAD src0_sel:DWORD src1_sel:BYTE_0
	s_movk_i32 s40, 0x400
	v_or3_b32 v5, v5, v7, v8
	v_bfe_i32 v16, v2, 0, 16
	v_add_u32_e32 v2, v15, v16
	v_mul_lo_u32 v5, v5, s40
	v_mul_lo_u32 v17, v6, s40
	v_add_lshl_u32 v130, v5, v2, 1
	v_add_lshl_u32 v132, v2, v17, 1
	v_bfe_i32 v2, v14, 27, 1
	v_lshrrev_b32_e32 v2, 22, v2
	v_add_u32_e32 v2, v0, v2
	v_and_b32_e32 v2, 0xfffffc00, v2
	v_sub_u32_e32 v0, v0, v2
	v_readlane_b32 s2, v249, 8
	v_lshrrev_b32_e32 v2, 4, v0
	v_ashrrev_i32_e32 v4, 31, v14
	v_readlane_b32 s3, v249, 9
	s_waitcnt lgkmcnt(0)
	s_add_u32 s1, s44, s2
	v_bitop3_b32 v0, v2, v0, 32 bitop3:0x6c
	v_lshrrev_b32_e32 v4, 26, v4
	s_addc_u32 s3, s45, s3
	v_ashrrev_i32_e32 v2, 31, v0
	v_add_u32_e32 v4, v14, v4
	s_add_u32 s2, s1, 0x6000000
	v_lshrrev_b32_e32 v2, 26, v2
	v_ashrrev_i32_e32 v4, 6, v4
	s_addc_u32 s3, s3, 0
	v_writelane_b32 v248, s18, 36
	s_mul_i32 s1, s18, 0x500000
	v_add_u32_e32 v2, v0, v2
	v_lshlrev_b32_e32 v5, 3, v4
	s_add_u32 s1, s44, s1
	v_ashrrev_i32_e32 v3, 6, v2
	v_and_b32_e32 v5, -16, v5
	s_addc_u32 s4, s45, 0
	v_add_u32_e32 v5, v3, v5
	v_and_b32_e32 v2, 0xc0, v2
	s_add_u32 s10, s1, 0x200000
	v_readfirstlane_b32 s1, v14
	v_and_b32_e32 v3, 3, v3
	v_lshrrev_b32_e32 v6, 2, v5
	v_lshlrev_b32_e32 v7, 1, v5
	v_sub_u32_e32 v0, v0, v2
	s_addc_u32 s11, s4, 0
	s_ashr_i32 s8, s1, 6
	v_and_or_b32 v3, v5, s5, v3
	v_and_b32_e32 v6, 4, v6
	v_and_b32_e32 v7, 24, v7
	v_lshlrev_b32_e32 v4, 5, v4
	v_ashrrev_i16_sdwa v0, v227, sext(v0) dst_sel:DWORD dst_unused:UNUSED_PAD src0_sel:DWORD src1_sel:BYTE_0
	s_lshl_b32 s4, s8, 10
	v_or3_b32 v3, v3, v6, v7
	v_and_b32_e32 v18, 32, v4
	v_bfe_i32 v19, v0, 0, 16
	v_mul_lo_u32 v3, v3, s40
	v_add_u32_e32 v2, v18, v19
	s_add_i32 s5, s4, 0
	s_ashr_i32 s41, s40, 31
	v_add_lshl_u32 v0, v3, v2, 1
	s_add_i32 m0, s5, 0x10000
	s_ashr_i32 s9, s1, 8
	s_lshl_b64 s[20:21], s[40:41], 8
	global_load_lds_dwordx4 v0, s[10:11]
	s_add_i32 m0, s5, 0x12000
	s_add_u32 s26, s10, s20
	global_load_lds_dwordx4 v130, s[10:11]
	s_addc_u32 s27, s11, s21
	s_add_i32 m0, s5, 0x14000
	v_writelane_b32 v248, s19, 37
	v_mul_lo_u32 v20, v5, s40
	global_load_lds_dwordx4 v0, s[26:27]
	s_add_i32 m0, s5, 0x16000
	s_add_i32 s18, s5, 0x2000
	v_add_lshl_u32 v134, v2, v20, 1
	global_load_lds_dwordx4 v130, s[26:27]
	s_mov_b32 m0, s5
	s_add_u32 s38, s2, s20
	global_load_lds_dwordx4 v134, s[2:3]
	s_mov_b32 m0, s18
	s_addc_u32 s39, s3, s21
	s_add_i32 s19, s5, 0x4000
	global_load_lds_dwordx4 v132, s[2:3]
	s_mov_b32 m0, s19
	s_add_i32 s52, s5, 0x6000
	global_load_lds_dwordx4 v134, s[38:39]
	s_mov_b32 m0, s52
	v_mov_b32_e32 v131, v1
	global_load_lds_dwordx4 v132, s[38:39]
	v_mov_b32_e32 v135, v1
	v_mov_b32_e32 v133, v1
	s_cmp_eq_u32 s9, 1
	v_lshl_add_u64 v[10:11], s[10:11], 0, v[0:1]
	v_lshl_add_u64 v[6:7], s[10:11], 0, v[130:131]
	v_lshl_add_u64 v[4:5], s[26:27], 0, v[0:1]
	v_lshl_add_u64 v[2:3], s[26:27], 0, v[130:131]
	v_lshl_add_u64 v[8:9], s[2:3], 0, v[134:135]
	s_cselect_b64 s[26:27], -1, 0
	s_cmp_lg_u32 s9, 1
	v_lshl_add_u64 v[12:13], s[2:3], 0, v[132:133]
	s_cbranch_scc1 .LBB0_124
	s_barrier
